# v49 + pre-norm row loads use the default cache policy instead of nontemporal
# baseline (speedup 1.0000x reference)
; DI unsigned pk2(float lo, float hi) { f32x2 v = {lo, hi}; bf16x2_t b = __builtin_convertvector(v, bf16x2_t); return __builtin_bit_cast(unsigned, b); }
; DI void norm_phase(Frame& F, const float* srcL, const float* srcC, const float* g, const float* modl, int sub) {
;     ...
;     for (int row = gw * RPW; row < gw * RPW + RPW; ++row) {
;         const int bi = row < TL ? (row >> 12) : 16;
;         if (bi != cur_bi) { cur_bi = bi; const float* mp = modl + (size_t)bi * MODW + sub * 3072;
; #pragma unroll
;             for (int j = 0; j < 4; ++j) { const int k = (F.lane + 64 * j) * 4; const f32x4 gg = *(const f32x4*)(g + k), sc = *(const f32x4*)(mp + 1024 + k); sh[j] = *(const f32x4*)(mp + k); gs[j] = gg * (sc + 1.0f); } }
;         const float* src = row < TL ? srcL + (size_t)row * DM : srcC + (size_t)(row - TL) * DM;
;         f32x4 v[4]; float ss = 0.f;
; #pragma unroll
;         for (int j = 0; j < 4; ++j) { v[j] = __builtin_nontemporal_load((const f32x4*)(src + (F.lane + 64 * j) * 4)); ss += (v[j][0] * v[j][0] + v[j][1] * v[j][1]) + (v[j][2] * v[j][2] + v[j][3] * v[j][3]); }
;         const float rstd = rsqrtf(wave_sum(ss) * (1.0f / DM) + EPS);
;         bf16_t* hp = H + (size_t)row * DM;
; #pragma unroll
;         for (int j = 0; j < 4; ++j) { const f32x4 o = v[j] * rstd * gs[j] + sh[j]; u32x2 w; w.x = pk2(o[0], o[1]); w.y = pk2(o[2], o[3]); *(u32x2*)(hp + (F.lane + 64 * j) * 4) = w; }
;     }
.LBB0_526:
	global_load_dwordx4 v[48:51], v0, s[62:63]
	global_load_dwordx4 v[52:55], v0, s[62:63] offset:1024
	global_load_dwordx4 v[56:59], v0, s[62:63] offset:3072
	global_load_dwordx4 v[60:63], v0, s[62:63] offset:2048
	s_lshl_b64 s[8:9], s[8:9], 11
	s_add_u32 s4, s4, 1
	s_addc_u32 s5, s5, 0
	s_add_u32 s6, s6, 0x1000
	s_addc_u32 s7, s7, 0
	s_add_i32 s16, s16, 1
	s_cmp_ge_i32 s16, s11
	s_waitcnt vmcnt(0)
	v_pk_mul_f32 v[64:65], v[50:51], v[50:51]
	v_pk_mul_f32 v[66:67], v[48:49], v[48:49]
	v_pk_mul_f32 v[68:69], v[54:55], v[54:55]
	v_pk_mul_f32 v[70:71], v[52:53], v[52:53]
	v_pk_mov_b32 v[74:75], v[66:67], v[64:65] op_sel:[1,0]
	v_mov_b32_e32 v67, v65
	v_pk_mov_b32 v[64:65], v[70:71], v[68:69] op_sel:[1,0]
	v_mov_b32_e32 v71, v69
	v_mul_f32_e32 v0, v61, v61
	v_mul_f32_e32 v72, v63, v63
	v_pk_add_f32 v[66:67], v[74:75], v[66:67]
	v_pk_add_f32 v[64:65], v[64:65], v[70:71]
	v_mul_f32_e32 v76, v56, v56
	v_mul_f32_e32 v77, v57, v57
	v_mul_f32_e32 v78, v58, v58
	v_mul_f32_e32 v79, v59, v59
	v_pk_fma_f32 v[68:69], v[60:61], v[60:61], v[0:1] op_sel_hi:[1,1,0]
	v_pk_fma_f32 v[72:73], v[62:63], v[62:63], v[72:73] op_sel_hi:[1,1,0]
	v_pk_add_f32 v[66:67], v[66:67], v[66:67] op_sel:[0,1] op_sel_hi:[1,0]
	v_pk_add_f32 v[64:65], v[64:65], v[64:65] op_sel:[0,1] op_sel_hi:[1,0]
	v_mov_b32_e32 v69, v78
	v_mov_b32_e32 v73, v79
	v_mov_b32_e32 v67, v76
	v_mov_b32_e32 v65, v77
	v_pk_add_f32 v[68:69], v[68:69], v[72:73]
	v_pk_add_f32 v[64:65], v[66:67], v[64:65]
	s_nop 0
	v_pk_add_f32 v[64:65], v[64:65], v[68:69]
	s_nop 0
	v_add_f32_e32 v0, v64, v65
	ds_bpermute_b32 v64, v35, v0
	s_waitcnt lgkmcnt(0)
	v_add_f32_e32 v0, v0, v64
	ds_bpermute_b32 v64, v40, v0
	s_waitcnt lgkmcnt(0)
	v_add_f32_e32 v0, v0, v64
	ds_bpermute_b32 v64, v41, v0
	s_waitcnt lgkmcnt(0)
	v_add_f32_e32 v0, v0, v64
	ds_bpermute_b32 v64, v42, v0
	s_waitcnt lgkmcnt(0)
	v_add_f32_e32 v0, v0, v64
	ds_bpermute_b32 v64, v43, v0
	s_waitcnt lgkmcnt(0)
	v_add_f32_e32 v0, v0, v64
	ds_bpermute_b32 v66, v44, v0
	v_lshl_add_u64 v[64:65], v[38:39], 0, s[8:9]
	s_waitcnt lgkmcnt(0)
	v_add_f32_e32 v0, v0, v66
	v_fmamk_f32 v0, v0, 0x3a800000, v162
	v_mul_f32_e32 v66, 0x4b800000, v0
	v_cmp_gt_f32_e32 vcc, s27, v0
	s_nop 1
	v_cndmask_b32_e32 v0, v0, v66, vcc
	v_rsq_f32_e32 v0, v0
	s_nop 0
	v_mul_f32_e32 v66, 0x45800000, v0
	v_cndmask_b32_e32 v0, v0, v66, vcc
	v_pk_mul_f32 v[48:49], v[48:49], v[0:1] op_sel_hi:[1,0]
	v_pk_mul_f32 v[50:51], v[50:51], v[0:1] op_sel_hi:[1,0]
	v_pk_mul_f32 v[52:53], v[52:53], v[0:1] op_sel_hi:[1,0]
	v_pk_mul_f32 v[54:55], v[54:55], v[0:1] op_sel_hi:[1,0]
	v_pk_mul_f32 v[60:61], v[60:61], v[0:1] op_sel_hi:[1,0]
	v_pk_mul_f32 v[62:63], v[62:63], v[0:1] op_sel_hi:[1,0]
	v_pk_mul_f32 v[56:57], v[56:57], v[0:1] op_sel_hi:[1,0]
	v_pk_mul_f32 v[58:59], v[58:59], v[0:1] op_sel_hi:[1,0]
	v_pk_fma_f32 v[50:51], v[4:5], v[50:51], v[32:33]
	v_pk_fma_f32 v[48:49], v[2:3], v[48:49], v[30:31]
	v_pk_fma_f32 v[54:55], v[8:9], v[54:55], v[24:25]
	v_pk_fma_f32 v[52:53], v[6:7], v[52:53], v[22:23]
	v_pk_fma_f32 v[62:63], v[12:13], v[62:63], v[20:21]
	v_pk_fma_f32 v[60:61], v[10:11], v[60:61], v[18:19]
	v_pk_fma_f32 v[58:59], v[16:17], v[58:59], v[28:29]
	v_pk_fma_f32 v[56:57], v[14:15], v[56:57], v[26:27]
	v_cvt_pk_bf16_f32 v48, v48, v49
	v_cvt_pk_bf16_f32 v49, v50, v51
	v_cvt_pk_bf16_f32 v50, v52, v53
	v_cvt_pk_bf16_f32 v51, v54, v55
	v_cvt_pk_bf16_f32 v52, v60, v61
	v_cvt_pk_bf16_f32 v53, v62, v63
	v_cvt_pk_bf16_f32 v54, v56, v57
	v_cvt_pk_bf16_f32 v55, v58, v59
	global_store_dwordx2 v[64:65], v[48:49], off
	global_store_dwordx2 v[64:65], v[50:51], off offset:512
	global_store_dwordx2 v[64:65], v[52:53], off offset:1024
	global_store_dwordx2 v[64:65], v[54:55], off offset:1536
	s_cbranch_scc1 .LBB0_531

; DI unsigned pk2(float lo, float hi) { f32x2 v = {lo, hi}; bf16x2_t b = __builtin_convertvector(v, bf16x2_t); return __builtin_bit_cast(unsigned, b); }
; DI void norm_pair_phase(Frame& F, const float* srcL, const float* srcC, const float* g, const float* modl, int sub) {
;     ...
;         const float* s1 = r1 < TL ? srcL + (size_t)r1 * DM : srcC + (size_t)(r1 - TL) * DM;
;         const float* s2 = r2 < TL ? srcL + (size_t)r2 * DM : srcC + (size_t)(r2 - TL) * DM;
;         f32x4 v1[4], v2[4]; float ss1 = 0.f, ss2 = 0.f;
; #pragma unroll
;         for (int q = 0; q < 4; ++q) { v1[q] = __builtin_nontemporal_load((const f32x4*)(s1 + (lane + 64 * q) * 4)); v2[q] = __builtin_nontemporal_load((const f32x4*)(s2 + (lane + 64 * q) * 4)); }
; #pragma unroll
;         for (int q = 0; q < 4; ++q) { ss1 += (v1[q][0] * v1[q][0] + v1[q][1] * v1[q][1]) + (v1[q][2] * v1[q][2] + v1[q][3] * v1[q][3]); ss2 += (v2[q][0] * v2[q][0] + v2[q][1] * v2[q][1]) + (v2[q][2] * v2[q][2] + v2[q][3] * v2[q][3]); }
; #pragma unroll
;         for (int o = 1; o < 64; o <<= 1) { ss1 += __shfl_xor(ss1, o); ss2 += __shfl_xor(ss2, o); }
;         const float rs1 = rsqrtf(ss1 * (1.0f / DM) + EPS), rs2 = rsqrtf(ss2 * (1.0f / DM) + EPS);
;         bf16_t* h1 = H + (size_t)r1 * DM; bf16_t* h2 = H + (size_t)r2 * DM;
;         bf16_t* hp = HS + (size_t)(isc ? r1 : bi * SEQ + j) * DM; bf16_t* hm = HS + (size_t)(isc ? r2 : bi * SEQ + 2048 + j) * DM;
; #pragma unroll
;         for (int q = 0; q < 4; ++q) {
;             const f32x4 o1 = v1[q] * rs1 * gs[q] + sh[q], o2 = v2[q] * rs2 * gs[q] + sh[q];
;             const int c = (lane + 64 * q) * 4;
;             u32x2 w; w.x = pk2(o1[0], o1[1]); w.y = pk2(o1[2], o1[3]); *(u32x2*)(h1 + c) = w;
;             if (!single) { u32x2 w2; w2.x = pk2(o2[0], o2[1]); w2.y = pk2(o2[2], o2[3]); *(u32x2*)(h2 + c) = w2; }
.LBB0_542:
	s_add_i32 s4, s66, 0xffff0000
	s_ashr_i32 s67, s66, 31
	global_load_dwordx4 v[58:61], v46, s[6:7]
	global_load_dwordx4 v[50:53], v46, s[6:7] offset:1024
	global_load_dwordx4 v[34:37], v46, s[6:7] offset:3072
	global_load_dwordx4 v[42:45], v46, s[6:7] offset:2048
	s_cmp_lt_i32 s66, 0x10000
	s_cselect_b32 s5, s67, 0
	s_cselect_b32 s4, s66, s4
	s_cselect_b32 s6, s55, s57
	s_cselect_b32 s7, s54, s56
	s_lshl_b64 s[4:5], s[4:5], 12
	s_add_u32 s4, s7, s4
	s_addc_u32 s5, s6, s5
	global_load_dwordx4 v[62:65], v46, s[4:5]
	global_load_dwordx4 v[54:57], v46, s[4:5] offset:1024
	global_load_dwordx4 v[38:41], v46, s[4:5] offset:3072
	s_nop 0
	global_load_dwordx4 v[46:49], v46, s[4:5] offset:2048
	s_lshl_b64 s[6:7], s[66:67], 11
	s_lshl_b64 s[28:29], s[68:69], 11
	s_add_u32 s70, s58, s28
	s_addc_u32 s71, s59, s29
	s_andn2_b64 vcc, exec, s[72:73]
	s_waitcnt vmcnt(0)
	v_pk_mul_f32 v[80:81], v[60:61], v[60:61]
	v_pk_mul_f32 v[82:83], v[58:59], v[58:59]
	v_pk_mul_f32 v[84:85], v[52:53], v[52:53]
	v_pk_mul_f32 v[86:87], v[50:51], v[50:51]
	v_pk_mov_b32 v[100:101], v[82:83], v[80:81] op_sel:[1,0]
	v_mov_b32_e32 v83, v81
	v_pk_mov_b32 v[80:81], v[86:87], v[84:85] op_sel:[1,0]
	v_mov_b32_e32 v87, v85
	v_mul_f32_e32 v91, v34, v34
	v_mul_f32_e32 v88, v43, v43
	v_mul_f32_e32 v90, v45, v45
	v_pk_add_f32 v[82:83], v[100:101], v[82:83]
	v_pk_add_f32 v[80:81], v[80:81], v[86:87]
	v_mul_f32_e32 v99, v35, v35
	v_mul_f32_e32 v102, v36, v36
	v_mul_f32_e32 v103, v37, v37
	v_pk_fma_f32 v[84:85], v[42:43], v[42:43], v[88:89] op_sel_hi:[1,1,0]
	v_pk_fma_f32 v[88:89], v[44:45], v[44:45], v[90:91] op_sel_hi:[1,1,0]
	v_pk_add_f32 v[82:83], v[82:83], v[82:83] op_sel:[0,1] op_sel_hi:[1,0]
	v_pk_add_f32 v[80:81], v[80:81], v[80:81] op_sel:[0,1] op_sel_hi:[1,0]
	v_mov_b32_e32 v85, v102
	v_mov_b32_e32 v89, v103
	v_mov_b32_e32 v83, v91
	v_mov_b32_e32 v81, v99
	v_pk_add_f32 v[84:85], v[84:85], v[88:89]
	v_pk_add_f32 v[80:81], v[82:83], v[80:81]
	v_pk_mul_f32 v[82:83], v[64:65], v[64:65]
	v_pk_mul_f32 v[86:87], v[62:63], v[62:63]
	v_pk_mul_f32 v[88:89], v[56:57], v[56:57]
	v_pk_mul_f32 v[90:91], v[54:55], v[54:55]
	v_pk_add_f32 v[80:81], v[80:81], v[84:85]
	v_pk_mov_b32 v[84:85], v[86:87], v[82:83] op_sel:[1,0]
	v_mov_b32_e32 v87, v83
	v_pk_mov_b32 v[82:83], v[90:91], v[88:89] op_sel:[1,0]
	v_mov_b32_e32 v91, v89
	v_mul_f32_e32 v103, v39, v39
	v_mul_f32_e32 v100, v47, v47
	v_mul_f32_e32 v102, v49, v49
	v_pk_add_f32 v[84:85], v[84:85], v[86:87]
	v_pk_add_f32 v[82:83], v[82:83], v[90:91]
	v_mul_f32_e32 v99, v38, v38
	v_mul_f32_e32 v104, v40, v40
	v_mul_f32_e32 v105, v41, v41
	v_pk_fma_f32 v[88:89], v[46:47], v[46:47], v[100:101] op_sel_hi:[1,1,0]
	v_pk_fma_f32 v[100:101], v[48:49], v[48:49], v[102:103] op_sel_hi:[1,1,0]
	v_pk_add_f32 v[84:85], v[84:85], v[84:85] op_sel:[0,1] op_sel_hi:[1,0]
	v_pk_add_f32 v[82:83], v[82:83], v[82:83] op_sel:[0,1] op_sel_hi:[1,0]
	v_mov_b32_e32 v89, v104
	v_mov_b32_e32 v101, v105
	v_mov_b32_e32 v85, v99
	v_mov_b32_e32 v83, v103
	v_pk_add_f32 v[86:87], v[88:89], v[100:101]
	v_pk_add_f32 v[82:83], v[84:85], v[82:83]
	v_mov_b32_e32 v102, v80
	v_pk_add_f32 v[82:83], v[82:83], v[86:87]
	v_cndmask_b32_e64 v84, 0, 1, s[72:73]
	v_mov_b32_e32 v103, v82
	v_mov_b32_e32 v82, v81
	v_pk_add_f32 v[80:81], v[102:103], v[82:83]
	ds_bpermute_b32 v83, v67, v81
	ds_bpermute_b32 v82, v67, v80
	v_cmp_ne_u32_e64 s[4:5], 1, v84
	v_lshlrev_b32_e32 v99, 1, v66
	s_waitcnt lgkmcnt(0)
	v_pk_add_f32 v[80:81], v[80:81], v[82:83]
	ds_bpermute_b32 v83, v92, v81
	ds_bpermute_b32 v82, v92, v80
	s_waitcnt lgkmcnt(0)
	v_pk_add_f32 v[80:81], v[80:81], v[82:83]
	ds_bpermute_b32 v83, v93, v81
	ds_bpermute_b32 v82, v93, v80
	s_waitcnt lgkmcnt(0)
	v_pk_add_f32 v[80:81], v[80:81], v[82:83]
	ds_bpermute_b32 v83, v94, v81
	ds_bpermute_b32 v82, v94, v80
	s_waitcnt lgkmcnt(0)
	v_pk_add_f32 v[80:81], v[80:81], v[82:83]
	ds_bpermute_b32 v83, v95, v81
	ds_bpermute_b32 v82, v95, v80
	s_waitcnt lgkmcnt(0)
	v_pk_add_f32 v[82:83], v[80:81], v[82:83]
	ds_bpermute_b32 v85, v96, v83
	ds_bpermute_b32 v84, v96, v82
	v_lshl_add_u64 v[80:81], v[72:73], 0, s[6:7]
	s_mov_b32 s6, 0x3a800000
	s_waitcnt lgkmcnt(0)
	v_pk_add_f32 v[82:83], v[82:83], v[84:85]
	s_nop 0
	v_pk_fma_f32 v[82:83], v[82:83], s[6:7], v[162:163] op_sel_hi:[1,0,0]
	s_nop 0
	v_mul_f32_e32 v84, 0x4b800000, v83
	v_mul_f32_e32 v85, 0x4b800000, v82
	v_cmp_gt_f32_e64 s[6:7], s27, v83
	v_cmp_gt_f32_e64 s[8:9], s27, v82
	s_nop 0
	v_cndmask_b32_e64 v83, v83, v84, s[6:7]
	v_cndmask_b32_e64 v82, v82, v85, s[8:9]
	v_rsq_f32_e32 v83, v83
	v_rsq_f32_e32 v82, v82
	v_mul_f32_e32 v84, 0x45800000, v83
	v_mul_f32_e32 v85, 0x45800000, v82
	v_cndmask_b32_e64 v84, v83, v84, s[6:7]
	v_cndmask_b32_e64 v82, v82, v85, s[8:9]
	v_pk_mul_f32 v[62:63], v[62:63], v[84:85] op_sel_hi:[1,0]
	v_pk_mul_f32 v[64:65], v[64:65], v[84:85] op_sel_hi:[1,0]
	v_pk_mul_f32 v[58:59], v[58:59], v[82:83] op_sel_hi:[1,0]
	v_pk_mul_f32 v[60:61], v[60:61], v[82:83] op_sel_hi:[1,0]
	v_pk_fma_f32 v[64:65], v[20:21], v[64:65], v[16:17]
	v_pk_fma_f32 v[62:63], v[18:19], v[62:63], v[14:15]
	v_pk_fma_f32 v[88:89], v[20:21], v[60:61], v[16:17]
	v_pk_fma_f32 v[86:87], v[18:19], v[58:59], v[14:15]
	v_cvt_pk_bf16_f32 v60, v62, v63
	v_cvt_pk_bf16_f32 v61, v64, v65
	v_cvt_pk_bf16_f32 v58, v86, v87
	v_cvt_pk_bf16_f32 v59, v88, v89
	global_store_dwordx2 v[80:81], v[60:61], off
	s_cbranch_vccnz .LBB0_544
	global_store_dwordx2 v99, v[58:59], s[70:71]
